# v6b + grid barrier: L1 invalidate issued at wait start instead of after release
# baseline (speedup 1.0000x reference)
; __device__ __forceinline__ unsigned xb_ld(unsigned* p)              { return __hip_atomic_load(p, __ATOMIC_RELAXED, __HIP_MEMORY_SCOPE_AGENT); }
; __device__ __forceinline__ unsigned xb_add(unsigned* p, unsigned v) { return __hip_atomic_fetch_add(p, v, __ATOMIC_RELAXED, __HIP_MEMORY_SCOPE_AGENT); }
; #define XB_SPIN(cond, bar) do { unsigned _sp = 0; while (cond) { __builtin_amdgcn_s_sleep(1); \
;     if ((++_sp & 255u) == 0u) { if (xb_ld(&(bar)[XB_TMO])) break; if (_sp > XB_SPIN_CAP) { atomicAdd(&(bar)[XB_TMO], 1u); break; } } } } while (0)
; __device__ __forceinline__ void xcd_barrier(const XcdBarrier& b) {
;     ...
;         __builtin_amdgcn_s_waitcnt(0);
;         unsigned nloc = b.st[0], nx = b.st[1];
;         if (nloc == 0u) { xcd_barrier_complete(bar, b.x, nloc, nx); b.st[0] = nloc; b.st[1] = nx; }
;         const unsigned old = xb_add(&bar[XB_XSUB(b.x)], 1u);
;         const unsigned gen = old / nloc;
;         if (old + 1u == (gen + 1u) * nloc) {
;             __builtin_amdgcn_fence(__ATOMIC_RELEASE, "agent");
;             asm volatile("s_waitcnt vmcnt(0)" ::: "memory");
;             const unsigned og = xb_add(&bar[XB_TOP], 1u);
;             const unsigned tg = og / nx;
;             if (og + 1u == (tg + 1u) * nx) xb_add(&bar[XB_TOPGEN], 1u);
;             else XB_SPIN(xb_ld(&bar[XB_TOPGEN]) == tg, bar);
;             __builtin_amdgcn_fence(__ATOMIC_ACQUIRE, "agent");
;             xb_add(&bar[XB_XGEN(b.x)], 1u);
;             asm volatile("s_waitcnt vmcnt(0)" ::: "memory");
;         } else {
;             XB_SPIN(xb_ld(&bar[XB_XGEN(b.x)]) == gen, bar);
.LBB0_117:
	v_readlane_b32 s6, v252, 7
	s_lshl_b32 s6, s6, 8
	s_add_u32 s6, s72, s6
	s_addc_u32 s7, s73, 0
	v_mov_b32_e32 v2, 0x1000
	v_mov_b32_e32 v4, 1
	global_atomic_add v4, v2, v4, s[6:7] offset:1024 sc0
	v_cvt_f32_u32_e32 v2, v3
	v_sub_u32_e32 v5, 0, v3
	v_rcp_iflag_f32_e32 v2, v2
	s_nop 0
	v_mul_f32_e32 v2, 0x4f7ffffe, v2
	v_cvt_u32_f32_e32 v2, v2
	v_mul_lo_u32 v5, v5, v2
	v_mul_hi_u32 v5, v2, v5
	v_add_u32_e32 v2, v2, v5
	s_waitcnt vmcnt(0)
	v_mul_hi_u32 v2, v4, v2
	v_mul_lo_u32 v5, v2, v3
	v_sub_u32_e32 v5, v4, v5
	v_add_u32_e32 v6, 1, v2
	v_cmp_ge_u32_e32 vcc, v5, v3
	v_add_u32_e32 v4, 1, v4
	s_nop 0
	v_cndmask_b32_e32 v2, v2, v6, vcc
	v_sub_u32_e32 v6, v5, v3
	v_cndmask_b32_e32 v5, v5, v6, vcc
	v_add_u32_e32 v6, 1, v2
	v_cmp_ge_u32_e32 vcc, v5, v3
	s_nop 1
	v_cndmask_b32_e32 v2, v2, v6, vcc
	v_mul_lo_u32 v5, v3, v2
	v_add_u32_e32 v3, v5, v3
	v_cmp_ne_u32_e32 vcc, v4, v3
	s_and_saveexec_b64 s[8:9], vcc
	s_xor_b64 s[8:9], exec, s[8:9]
	s_cbranch_execz .LBB0_131
	s_waitcnt lgkmcnt(0)
	v_mov_b32_e32 v1, 0x2000
	buffer_inv sc1
	global_load_dword v1, v1, s[6:7] offset:1024 sc1
	s_add_u32 s16, s6, 0x2400
	s_addc_u32 s17, s7, 0
	s_waitcnt vmcnt(0)
	v_cmp_eq_u32_e32 vcc, v1, v2
	s_and_saveexec_b64 s[10:11], vcc
	s_cbranch_execz .LBB0_130
	s_add_u32 s14, s30, 0x1200
	s_addc_u32 s15, s31, 0
	s_mov_b32 s12, 1
	s_mov_b64 s[18:19], 0
	v_mov_b32_e32 v1, 0
	s_branch .LBB0_121

; __device__ __forceinline__ unsigned xb_add(unsigned* p, unsigned v) { return __hip_atomic_fetch_add(p, v, __ATOMIC_RELAXED, __HIP_MEMORY_SCOPE_AGENT); }
; __device__ __forceinline__ void xcd_barrier(const XcdBarrier& b) {
;     ...
;         const unsigned old = xb_add(&bar[XB_XSUB(b.x)], 1u);
;         const unsigned gen = old / nloc;
;         if (old + 1u == (gen + 1u) * nloc) {
;             __builtin_amdgcn_fence(__ATOMIC_RELEASE, "agent");
;             asm volatile("s_waitcnt vmcnt(0)" ::: "memory");
;             const unsigned og = xb_add(&bar[XB_TOP], 1u);
;             const unsigned tg = og / nx;
;             if (og + 1u == (tg + 1u) * nx) xb_add(&bar[XB_TOPGEN], 1u);
.LBB0_130:
	s_or_b64 exec, exec, s[10:11]
	s_waitcnt vmcnt(0)
	s_waitcnt vmcnt(0)
.LBB0_131:
	s_andn2_saveexec_b64 s[8:9], s[8:9]
	s_cbranch_execz .LBB0_149
	s_mov_b64 s[8:9], exec
	buffer_inv sc1
	buffer_wbl2 sc1
	s_waitcnt lgkmcnt(0)
	s_waitcnt vmcnt(0)
	v_mbcnt_lo_u32_b32 v2, s8, 0
	v_mbcnt_hi_u32_b32 v2, s9, v2
	v_cmp_eq_u32_e32 vcc, 0, v2
	s_and_saveexec_b64 s[10:11], vcc
	s_cbranch_execz .LBB0_134
	s_bcnt1_i32_b64 s8, s[8:9]
	v_mov_b32_e32 v3, 0x4000
	v_mov_b32_e32 v4, s8
	global_atomic_add v3, v3, v4, s[30:31] offset:1024 sc0

; __device__ __forceinline__ unsigned xb_ld(unsigned* p)              { return __hip_atomic_load(p, __ATOMIC_RELAXED, __HIP_MEMORY_SCOPE_AGENT); }
; __device__ __forceinline__ unsigned xb_add(unsigned* p, unsigned v) { return __hip_atomic_fetch_add(p, v, __ATOMIC_RELAXED, __HIP_MEMORY_SCOPE_AGENT); }
; #define XB_SPIN(cond, bar) do { unsigned _sp = 0; while (cond) { __builtin_amdgcn_s_sleep(1); \
;     if ((++_sp & 255u) == 0u) { if (xb_ld(&(bar)[XB_TMO])) break; if (_sp > XB_SPIN_CAP) { atomicAdd(&(bar)[XB_TMO], 1u); break; } } } } while (0)
; __device__ __forceinline__ void xcd_barrier(const XcdBarrier& b) {
;     ...
;             if (og + 1u == (tg + 1u) * nx) xb_add(&bar[XB_TOPGEN], 1u);
;             else XB_SPIN(xb_ld(&bar[XB_TOPGEN]) == tg, bar);
;             __builtin_amdgcn_fence(__ATOMIC_ACQUIRE, "agent");
;             xb_add(&bar[XB_XGEN(b.x)], 1u);
;             asm volatile("s_waitcnt vmcnt(0)" ::: "memory");
.LBB0_148:
	s_or_b64 exec, exec, s[8:9]
	v_mov_b32_e32 v1, 0x2000
	v_mov_b32_e32 v2, 1
	s_waitcnt vmcnt(0)
	global_atomic_add v1, v2, s[6:7] offset:1024
	s_waitcnt vmcnt(0)

; __device__ __forceinline__ unsigned xb_ld(unsigned* p)              { return __hip_atomic_load(p, __ATOMIC_RELAXED, __HIP_MEMORY_SCOPE_AGENT); }
; __device__ __forceinline__ unsigned xb_add(unsigned* p, unsigned v) { return __hip_atomic_fetch_add(p, v, __ATOMIC_RELAXED, __HIP_MEMORY_SCOPE_AGENT); }
; #define XB_SPIN(cond, bar) do { unsigned _sp = 0; while (cond) { __builtin_amdgcn_s_sleep(1); \
;     if ((++_sp & 255u) == 0u) { if (xb_ld(&(bar)[XB_TMO])) break; if (_sp > XB_SPIN_CAP) { atomicAdd(&(bar)[XB_TMO], 1u); break; } } } } while (0)
; __device__ __forceinline__ void xcd_barrier(const XcdBarrier& b) {
;     ...
;         __builtin_amdgcn_s_waitcnt(0);
;         unsigned nloc = b.st[0], nx = b.st[1];
;         if (nloc == 0u) { xcd_barrier_complete(bar, b.x, nloc, nx); b.st[0] = nloc; b.st[1] = nx; }
;         const unsigned old = xb_add(&bar[XB_XSUB(b.x)], 1u);
;         const unsigned gen = old / nloc;
;         if (old + 1u == (gen + 1u) * nloc) {
;             __builtin_amdgcn_fence(__ATOMIC_RELEASE, "agent");
;             asm volatile("s_waitcnt vmcnt(0)" ::: "memory");
;             const unsigned og = xb_add(&bar[XB_TOP], 1u);
;             const unsigned tg = og / nx;
;             if (og + 1u == (tg + 1u) * nx) xb_add(&bar[XB_TOPGEN], 1u);
;             else XB_SPIN(xb_ld(&bar[XB_TOPGEN]) == tg, bar);
;             __builtin_amdgcn_fence(__ATOMIC_ACQUIRE, "agent");
;             xb_add(&bar[XB_XGEN(b.x)], 1u);
;             asm volatile("s_waitcnt vmcnt(0)" ::: "memory");
;         } else {
;             XB_SPIN(xb_ld(&bar[XB_XGEN(b.x)]) == gen, bar);
.LBB0_189:
	s_lshl_b32 s4, s33, 8
	s_add_u32 s4, s72, s4
	s_addc_u32 s5, s73, 0
	v_mov_b32_e32 v2, 0x1000
	v_mov_b32_e32 v4, 1
	global_atomic_add v4, v2, v4, s[4:5] offset:1024 sc0
	v_cvt_f32_u32_e32 v2, v3
	v_sub_u32_e32 v5, 0, v3
	v_rcp_iflag_f32_e32 v2, v2
	s_nop 0
	v_mul_f32_e32 v2, 0x4f7ffffe, v2
	v_cvt_u32_f32_e32 v2, v2
	v_mul_lo_u32 v5, v5, v2
	v_mul_hi_u32 v5, v2, v5
	v_add_u32_e32 v2, v2, v5
	s_waitcnt vmcnt(0)
	v_mul_hi_u32 v2, v4, v2
	v_mul_lo_u32 v5, v2, v3
	v_sub_u32_e32 v5, v4, v5
	v_add_u32_e32 v6, 1, v2
	v_cmp_ge_u32_e32 vcc, v5, v3
	v_add_u32_e32 v4, 1, v4
	s_nop 0
	v_cndmask_b32_e32 v2, v2, v6, vcc
	v_sub_u32_e32 v6, v5, v3
	v_cndmask_b32_e32 v5, v5, v6, vcc
	v_add_u32_e32 v6, 1, v2
	v_cmp_ge_u32_e32 vcc, v5, v3
	s_nop 1
	v_cndmask_b32_e32 v2, v2, v6, vcc
	v_mul_lo_u32 v5, v3, v2
	v_add_u32_e32 v3, v5, v3
	v_cmp_ne_u32_e32 vcc, v4, v3
	s_and_saveexec_b64 s[6:7], vcc
	s_xor_b64 s[6:7], exec, s[6:7]
	s_cbranch_execz .LBB0_203
	s_waitcnt lgkmcnt(0)
	v_mov_b32_e32 v1, 0x2000
	buffer_inv sc1
	global_load_dword v1, v1, s[4:5] offset:1024 sc1
	s_add_u32 s14, s4, 0x2400
	s_addc_u32 s15, s5, 0
	s_waitcnt vmcnt(0)
	v_cmp_eq_u32_e32 vcc, v1, v2
	s_and_saveexec_b64 s[8:9], vcc
	s_cbranch_execz .LBB0_202
	s_add_u32 s10, s30, 0x1200
	s_addc_u32 s11, s31, 0
	s_mov_b32 s12, 1
	s_mov_b64 s[16:17], 0
	v_mov_b32_e32 v1, 0
	s_branch .LBB0_193

; __device__ __forceinline__ unsigned xb_add(unsigned* p, unsigned v) { return __hip_atomic_fetch_add(p, v, __ATOMIC_RELAXED, __HIP_MEMORY_SCOPE_AGENT); }
; __device__ __forceinline__ void xcd_barrier(const XcdBarrier& b) {
;     ...
;         const unsigned old = xb_add(&bar[XB_XSUB(b.x)], 1u);
;         const unsigned gen = old / nloc;
;         if (old + 1u == (gen + 1u) * nloc) {
;             __builtin_amdgcn_fence(__ATOMIC_RELEASE, "agent");
;             asm volatile("s_waitcnt vmcnt(0)" ::: "memory");
;             const unsigned og = xb_add(&bar[XB_TOP], 1u);
;             const unsigned tg = og / nx;
;             if (og + 1u == (tg + 1u) * nx) xb_add(&bar[XB_TOPGEN], 1u);
.LBB0_202:
	s_or_b64 exec, exec, s[8:9]
	s_waitcnt vmcnt(0)
	s_waitcnt vmcnt(0)
.LBB0_203:
	s_andn2_saveexec_b64 s[6:7], s[6:7]
	s_cbranch_execz .LBB0_221
	s_mov_b64 s[6:7], exec
	buffer_inv sc1
	buffer_wbl2 sc1
	s_waitcnt lgkmcnt(0)
	s_waitcnt vmcnt(0)
	v_mbcnt_lo_u32_b32 v2, s6, 0
	v_mbcnt_hi_u32_b32 v2, s7, v2
	v_cmp_eq_u32_e32 vcc, 0, v2
	s_and_saveexec_b64 s[8:9], vcc
	s_cbranch_execz .LBB0_206
	s_bcnt1_i32_b64 s6, s[6:7]
	v_mov_b32_e32 v3, 0x4000
	v_mov_b32_e32 v4, s6
	global_atomic_add v3, v3, v4, s[30:31] offset:1024 sc0

; __device__ __forceinline__ unsigned xb_ld(unsigned* p)              { return __hip_atomic_load(p, __ATOMIC_RELAXED, __HIP_MEMORY_SCOPE_AGENT); }
; __device__ __forceinline__ unsigned xb_add(unsigned* p, unsigned v) { return __hip_atomic_fetch_add(p, v, __ATOMIC_RELAXED, __HIP_MEMORY_SCOPE_AGENT); }
; #define XB_SPIN(cond, bar) do { unsigned _sp = 0; while (cond) { __builtin_amdgcn_s_sleep(1); \
;     if ((++_sp & 255u) == 0u) { if (xb_ld(&(bar)[XB_TMO])) break; if (_sp > XB_SPIN_CAP) { atomicAdd(&(bar)[XB_TMO], 1u); break; } } } } while (0)
; __device__ __forceinline__ void xcd_barrier(const XcdBarrier& b) {
;     ...
;             if (og + 1u == (tg + 1u) * nx) xb_add(&bar[XB_TOPGEN], 1u);
;             else XB_SPIN(xb_ld(&bar[XB_TOPGEN]) == tg, bar);
;             __builtin_amdgcn_fence(__ATOMIC_ACQUIRE, "agent");
;             xb_add(&bar[XB_XGEN(b.x)], 1u);
;             asm volatile("s_waitcnt vmcnt(0)" ::: "memory");
.LBB0_220:
	s_or_b64 exec, exec, s[6:7]
	v_mov_b32_e32 v1, 0x2000
	v_mov_b32_e32 v2, 1
	s_waitcnt vmcnt(0)
	global_atomic_add v1, v2, s[4:5] offset:1024
	s_waitcnt vmcnt(0)

; __device__ __forceinline__ unsigned xb_add(unsigned* p, unsigned v) { return __hip_atomic_fetch_add(p, v, __ATOMIC_RELAXED, __HIP_MEMORY_SCOPE_AGENT); }
; __device__ __forceinline__ void xcd_barrier(const XcdBarrier& b) {
;     ...
;             __builtin_amdgcn_fence(__ATOMIC_ACQUIRE, "agent");
;             xb_add(&bar[XB_XGEN(b.x)], 1u);
;             asm volatile("s_waitcnt vmcnt(0)" ::: "memory");
.LBB0_223:
	s_or_b64 exec, exec, s[4:5]
	v_readlane_b32 s4, v253, 59
	v_readlane_b32 s5, v253, 60
	s_waitcnt vmcnt(0)
	s_nop 2
	global_atomic_add v3, v1, s[4:5]
	s_waitcnt vmcnt(0)

; __device__ __forceinline__ unsigned xb_ld(unsigned* p)              { return __hip_atomic_load(p, __ATOMIC_RELAXED, __HIP_MEMORY_SCOPE_AGENT); }
; __device__ __forceinline__ unsigned xb_add(unsigned* p, unsigned v) { return __hip_atomic_fetch_add(p, v, __ATOMIC_RELAXED, __HIP_MEMORY_SCOPE_AGENT); }
; #define XB_SPIN(cond, bar) do { unsigned _sp = 0; while (cond) { __builtin_amdgcn_s_sleep(1); \
;     if ((++_sp & 255u) == 0u) { if (xb_ld(&(bar)[XB_TMO])) break; if (_sp > XB_SPIN_CAP) { atomicAdd(&(bar)[XB_TMO], 1u); break; } } } } while (0)
; __device__ __forceinline__ void xcd_barrier(const XcdBarrier& b) {
;     ...
;         unsigned nloc = b.st[0], nx = b.st[1];
;         if (nloc == 0u) { xcd_barrier_complete(bar, b.x, nloc, nx); b.st[0] = nloc; b.st[1] = nx; }
;         const unsigned old = xb_add(&bar[XB_XSUB(b.x)], 1u);
;         const unsigned gen = old / nloc;
;         if (old + 1u == (gen + 1u) * nloc) {
;             __builtin_amdgcn_fence(__ATOMIC_RELEASE, "agent");
;             asm volatile("s_waitcnt vmcnt(0)" ::: "memory");
;             const unsigned og = xb_add(&bar[XB_TOP], 1u);
;             const unsigned tg = og / nx;
;             if (og + 1u == (tg + 1u) * nx) xb_add(&bar[XB_TOPGEN], 1u);
;             else XB_SPIN(xb_ld(&bar[XB_TOPGEN]) == tg, bar);
;             __builtin_amdgcn_fence(__ATOMIC_ACQUIRE, "agent");
;             xb_add(&bar[XB_XGEN(b.x)], 1u);
;             asm volatile("s_waitcnt vmcnt(0)" ::: "memory");
;         } else {
;             XB_SPIN(xb_ld(&bar[XB_XGEN(b.x)]) == gen, bar);
.LBB0_297:
	v_readlane_b32 s4, v253, 57
	v_readlane_b32 s5, v253, 58
	v_cvt_f32_u32_e32 v2, v5
	v_sub_u32_e32 v7, 0, v5
	v_rcp_iflag_f32_e32 v2, v2
	s_nop 1
	global_atomic_add v6, v3, v1, s[4:5] sc0
	v_mul_f32_e32 v2, 0x4f7ffffe, v2
	v_cvt_u32_f32_e32 v2, v2
	v_mul_lo_u32 v7, v7, v2
	v_mul_hi_u32 v7, v2, v7
	v_add_u32_e32 v2, v2, v7
	s_waitcnt vmcnt(0)
	v_mul_hi_u32 v2, v6, v2
	v_mul_lo_u32 v7, v2, v5
	v_sub_u32_e32 v7, v6, v7
	v_add_u32_e32 v8, 1, v2
	v_cmp_ge_u32_e32 vcc, v7, v5
	v_add_u32_e32 v6, 1, v6
	s_nop 0
	v_cndmask_b32_e32 v2, v2, v8, vcc
	v_sub_u32_e32 v8, v7, v5
	v_cndmask_b32_e32 v7, v7, v8, vcc
	v_add_u32_e32 v8, 1, v2
	v_cmp_ge_u32_e32 vcc, v7, v5
	s_nop 1
	v_cndmask_b32_e32 v2, v2, v8, vcc
	v_mul_lo_u32 v7, v5, v2
	v_add_u32_e32 v5, v7, v5
	v_cmp_ne_u32_e32 vcc, v6, v5
	s_and_saveexec_b64 s[4:5], vcc
	s_xor_b64 s[4:5], exec, s[4:5]
	s_cbranch_execz .LBB0_311
	v_readlane_b32 s6, v253, 59
	v_readlane_b32 s7, v253, 60
	s_waitcnt lgkmcnt(0)
	s_nop 3
	buffer_inv sc1
	global_load_dword v4, v3, s[6:7] sc1
	s_waitcnt vmcnt(0)
	v_cmp_eq_u32_e32 vcc, v4, v2
	s_and_saveexec_b64 s[6:7], vcc
	s_cbranch_execz .LBB0_310
	s_mov_b32 s12, 1
	s_mov_b64 s[8:9], 0
	s_branch .LBB0_301

; __device__ __forceinline__ unsigned xb_add(unsigned* p, unsigned v) { return __hip_atomic_fetch_add(p, v, __ATOMIC_RELAXED, __HIP_MEMORY_SCOPE_AGENT); }
; __device__ __forceinline__ void xcd_barrier(const XcdBarrier& b) {
;     ...
;         const unsigned old = xb_add(&bar[XB_XSUB(b.x)], 1u);
;         const unsigned gen = old / nloc;
;         if (old + 1u == (gen + 1u) * nloc) {
;             __builtin_amdgcn_fence(__ATOMIC_RELEASE, "agent");
;             asm volatile("s_waitcnt vmcnt(0)" ::: "memory");
;             const unsigned og = xb_add(&bar[XB_TOP], 1u);
;             const unsigned tg = og / nx;
;             if (og + 1u == (tg + 1u) * nx) xb_add(&bar[XB_TOPGEN], 1u);
.LBB0_310:
	s_or_b64 exec, exec, s[6:7]
	s_waitcnt vmcnt(0)
	s_waitcnt vmcnt(0)
.LBB0_311:
	s_andn2_saveexec_b64 s[4:5], s[4:5]
	s_cbranch_execz .LBB0_329
	s_mov_b64 s[4:5], exec
	buffer_inv sc1
	buffer_wbl2 sc1
	s_waitcnt lgkmcnt(0)
	s_waitcnt vmcnt(0)
	v_mbcnt_lo_u32_b32 v2, s4, 0
	v_mbcnt_hi_u32_b32 v2, s5, v2
	v_cmp_eq_u32_e32 vcc, 0, v2
	s_and_saveexec_b64 s[6:7], vcc
	s_cbranch_execz .LBB0_314
	s_bcnt1_i32_b64 s4, s[4:5]
	v_mov_b32_e32 v5, s4
	v_readlane_b32 s4, v253, 61
	v_readlane_b32 s5, v253, 62
	s_nop 4
	global_atomic_add v5, v3, v5, s[4:5] sc0

; __device__ __forceinline__ unsigned xb_ld(unsigned* p)              { return __hip_atomic_load(p, __ATOMIC_RELAXED, __HIP_MEMORY_SCOPE_AGENT); }
; __device__ __forceinline__ unsigned xb_add(unsigned* p, unsigned v) { return __hip_atomic_fetch_add(p, v, __ATOMIC_RELAXED, __HIP_MEMORY_SCOPE_AGENT); }
; #define XB_SPIN(cond, bar) do { unsigned _sp = 0; while (cond) { __builtin_amdgcn_s_sleep(1); \
;     if ((++_sp & 255u) == 0u) { if (xb_ld(&(bar)[XB_TMO])) break; if (_sp > XB_SPIN_CAP) { atomicAdd(&(bar)[XB_TMO], 1u); break; } } } } while (0)
; __device__ __forceinline__ void xcd_barrier(const XcdBarrier& b) {
;     ...
;         unsigned nloc = b.st[0], nx = b.st[1];
;         if (nloc == 0u) { xcd_barrier_complete(bar, b.x, nloc, nx); b.st[0] = nloc; b.st[1] = nx; }
;         const unsigned old = xb_add(&bar[XB_XSUB(b.x)], 1u);
;         const unsigned gen = old / nloc;
;         if (old + 1u == (gen + 1u) * nloc) {
;             __builtin_amdgcn_fence(__ATOMIC_RELEASE, "agent");
;             asm volatile("s_waitcnt vmcnt(0)" ::: "memory");
;             const unsigned og = xb_add(&bar[XB_TOP], 1u);
;             const unsigned tg = og / nx;
;             if (og + 1u == (tg + 1u) * nx) xb_add(&bar[XB_TOPGEN], 1u);
;             else XB_SPIN(xb_ld(&bar[XB_TOPGEN]) == tg, bar);
;             __builtin_amdgcn_fence(__ATOMIC_ACQUIRE, "agent");
;             xb_add(&bar[XB_XGEN(b.x)], 1u);
;             asm volatile("s_waitcnt vmcnt(0)" ::: "memory");
;         } else {
;             XB_SPIN(xb_ld(&bar[XB_XGEN(b.x)]) == gen, bar);
.LBB0_478:
	v_readlane_b32 s4, v253, 57
	v_readlane_b32 s5, v253, 58
	v_cvt_f32_u32_e32 v2, v5
	v_sub_u32_e32 v7, 0, v5
	v_rcp_iflag_f32_e32 v2, v2
	s_nop 1
	global_atomic_add v6, v3, v1, s[4:5] sc0
	v_mul_f32_e32 v2, 0x4f7ffffe, v2
	v_cvt_u32_f32_e32 v2, v2
	v_mul_lo_u32 v7, v7, v2
	v_mul_hi_u32 v7, v2, v7
	v_add_u32_e32 v2, v2, v7
	s_waitcnt vmcnt(0)
	v_mul_hi_u32 v2, v6, v2
	v_mul_lo_u32 v7, v2, v5
	v_sub_u32_e32 v7, v6, v7
	v_add_u32_e32 v8, 1, v2
	v_cmp_ge_u32_e32 vcc, v7, v5
	v_add_u32_e32 v6, 1, v6
	s_nop 0
	v_cndmask_b32_e32 v2, v2, v8, vcc
	v_sub_u32_e32 v8, v7, v5
	v_cndmask_b32_e32 v7, v7, v8, vcc
	v_add_u32_e32 v8, 1, v2
	v_cmp_ge_u32_e32 vcc, v7, v5
	s_nop 1
	v_cndmask_b32_e32 v2, v2, v8, vcc
	v_mul_lo_u32 v7, v5, v2
	v_add_u32_e32 v5, v7, v5
	v_cmp_ne_u32_e32 vcc, v6, v5
	s_and_saveexec_b64 s[4:5], vcc
	s_xor_b64 s[4:5], exec, s[4:5]
	s_cbranch_execz .LBB0_492
	v_readlane_b32 s6, v253, 59
	v_readlane_b32 s7, v253, 60
	s_waitcnt lgkmcnt(0)
	s_nop 3
	buffer_inv sc1
	global_load_dword v4, v3, s[6:7] sc1
	s_waitcnt vmcnt(0)
	v_cmp_eq_u32_e32 vcc, v4, v2
	s_and_saveexec_b64 s[6:7], vcc
	s_cbranch_execz .LBB0_491
	s_mov_b32 s10, 1
	s_mov_b64 s[8:9], 0
	s_branch .LBB0_482

; __device__ __forceinline__ unsigned xb_ld(unsigned* p)              { return __hip_atomic_load(p, __ATOMIC_RELAXED, __HIP_MEMORY_SCOPE_AGENT); }
; __device__ __forceinline__ unsigned xb_add(unsigned* p, unsigned v) { return __hip_atomic_fetch_add(p, v, __ATOMIC_RELAXED, __HIP_MEMORY_SCOPE_AGENT); }
; #define XB_SPIN(cond, bar) do { unsigned _sp = 0; while (cond) { __builtin_amdgcn_s_sleep(1); \
;     if ((++_sp & 255u) == 0u) { if (xb_ld(&(bar)[XB_TMO])) break; if (_sp > XB_SPIN_CAP) { atomicAdd(&(bar)[XB_TMO], 1u); break; } } } } while (0)
; __device__ __forceinline__ void xcd_barrier(const XcdBarrier& b) {
;     ...
;         unsigned nloc = b.st[0], nx = b.st[1];
;         if (nloc == 0u) { xcd_barrier_complete(bar, b.x, nloc, nx); b.st[0] = nloc; b.st[1] = nx; }
;         const unsigned old = xb_add(&bar[XB_XSUB(b.x)], 1u);
;         const unsigned gen = old / nloc;
;         if (old + 1u == (gen + 1u) * nloc) {
;             __builtin_amdgcn_fence(__ATOMIC_RELEASE, "agent");
;             asm volatile("s_waitcnt vmcnt(0)" ::: "memory");
;             const unsigned og = xb_add(&bar[XB_TOP], 1u);
;             const unsigned tg = og / nx;
;             if (og + 1u == (tg + 1u) * nx) xb_add(&bar[XB_TOPGEN], 1u);
;             else XB_SPIN(xb_ld(&bar[XB_TOPGEN]) == tg, bar);
;             __builtin_amdgcn_fence(__ATOMIC_ACQUIRE, "agent");
;             xb_add(&bar[XB_XGEN(b.x)], 1u);
;             asm volatile("s_waitcnt vmcnt(0)" ::: "memory");
;         } else {
;             XB_SPIN(xb_ld(&bar[XB_XGEN(b.x)]) == gen, bar);
.LBB0_677:
	s_or_b64 exec, exec, s[6:7]
	s_waitcnt vmcnt(0)
	v_readfirstlane_b32 s4, v5
	v_sub_u32_e32 v6, 0, v4
	s_mov_b64 s[6:7], -1
	v_add_u32_e32 v5, s4, v2
	v_cvt_f32_u32_e32 v2, v4
	v_readlane_b32 s4, v253, 63
	v_readlane_b32 s5, v254, 0
	v_rcp_iflag_f32_e32 v2, v2
	s_nop 0
	v_mul_f32_e32 v2, 0x4f7ffffe, v2
	v_cvt_u32_f32_e32 v2, v2
	v_mul_lo_u32 v6, v6, v2
	v_mul_hi_u32 v6, v2, v6
	v_add_u32_e32 v2, v2, v6
	v_mul_hi_u32 v2, v5, v2
	v_mul_lo_u32 v6, v2, v4
	v_sub_u32_e32 v6, v5, v6
	v_cmp_ge_u32_e32 vcc, v6, v4
	v_add_u32_e32 v7, 1, v2
	v_add_u32_e32 v5, 1, v5
	v_cndmask_b32_e32 v2, v2, v7, vcc
	v_sub_u32_e32 v7, v6, v4
	v_cndmask_b32_e32 v6, v6, v7, vcc
	v_cmp_ge_u32_e32 vcc, v6, v4
	v_add_u32_e32 v6, 1, v2
	s_nop 0
	v_cndmask_b32_e32 v2, v2, v6, vcc
	v_mul_lo_u32 v6, v4, v2
	v_add_u32_e32 v4, v6, v4
	v_cmp_ne_u32_e32 vcc, v5, v4
	v_mov_b64_e32 v[4:5], s[4:5]
	s_and_saveexec_b64 s[4:5], vcc
	s_cbranch_execz .LBB0_706
	v_readlane_b32 s6, v253, 63
	v_readlane_b32 s7, v254, 0
	s_mov_b64 s[8:9], 0
	s_nop 3
	buffer_inv sc1
	global_load_dword v4, v3, s[6:7] sc1
	s_waitcnt vmcnt(0)
	v_cmp_eq_u32_e32 vcc, v4, v2
	s_and_saveexec_b64 s[6:7], vcc
	s_cbranch_execz .LBB0_705
	s_mov_b32 s10, 1
	s_branch .LBB0_681

; __device__ __forceinline__ unsigned xb_add(unsigned* p, unsigned v) { return __hip_atomic_fetch_add(p, v, __ATOMIC_RELAXED, __HIP_MEMORY_SCOPE_AGENT); }
; __device__ __forceinline__ void xcd_barrier(const XcdBarrier& b) {
;     ...
;         if (old + 1u == (gen + 1u) * nloc) {
;             __builtin_amdgcn_fence(__ATOMIC_RELEASE, "agent");
;             asm volatile("s_waitcnt vmcnt(0)" ::: "memory");
;             const unsigned og = xb_add(&bar[XB_TOP], 1u);
;             const unsigned tg = og / nx;
;             if (og + 1u == (tg + 1u) * nx) xb_add(&bar[XB_TOPGEN], 1u);
.LBB0_1418:
	s_mov_b64 s[4:5], exec
	buffer_inv sc1
	buffer_wbl2 sc1
	s_waitcnt lgkmcnt(0)
	s_waitcnt vmcnt(0)
	v_mbcnt_lo_u32_b32 v2, s4, 0
	v_mbcnt_hi_u32_b32 v2, s5, v2
	v_cmp_eq_u32_e32 vcc, 0, v2
	s_and_saveexec_b64 s[6:7], vcc
	s_cbranch_execz .LBB0_1420
	s_bcnt1_i32_b64 s4, s[4:5]
	v_mov_b32_e32 v5, s4
	v_readlane_b32 s4, v253, 61
	v_readlane_b32 s5, v253, 62
	s_nop 4
	global_atomic_add v5, v3, v5, s[4:5] sc0
